# ATT0 key/value loop: waves 4-7 run half an iteration behind waves 0-3 (extra mid-iteration barrier, waves 0-3 stage the whole next tile) so the two waves of a SIMD alternate MFMA and softmax phases
# baseline (speedup 1.0000x reference)
.LBB0_326:
	s_or_b64 exec, exec, s[4:5]
	v_readlane_b32 s0, v219, 9
	v_lshlrev_b32_e32 v20, 2, v149
	v_readlane_b32 s8, v219, 17
	v_readlane_b32 s9, v219, 18
	s_waitcnt lgkmcnt(0)
	s_barrier
	v_readfirstlane_b32 s99, v168
	s_nop 1
	s_lshr_b32 s99, s99, 8
	s_nop 2
	global_load_dword v0, v20, s[8:9]
	global_load_dword v1, v20, s[8:9] offset:256
	global_load_dword v2, v20, s[8:9] offset:512
	global_load_dword v3, v20, s[8:9] offset:768
	v_mbcnt_hi_u32_b32 v4, -1, v163
	v_and_b32_e32 v5, 64, v4
	v_xor_b32_e32 v6, 32, v4
	v_add_u32_e32 v5, 64, v5
	v_cmp_lt_i32_e32 vcc, v6, v5
	v_xor_b32_e32 v7, 16, v4
	v_xor_b32_e32 v8, 8, v4
	v_cndmask_b32_e32 v6, v4, v6, vcc
	v_lshlrev_b32_e32 v172, 2, v6
	v_cmp_lt_i32_e32 vcc, v7, v5
	v_xor_b32_e32 v9, 4, v4
	v_xor_b32_e32 v10, 2, v4
	v_cndmask_b32_e32 v7, v4, v7, vcc
	v_lshlrev_b32_e32 v173, 2, v7
	v_cmp_lt_i32_e32 vcc, v8, v5
	v_xor_b32_e32 v11, 1, v4
	s_bcnt1_i32_b32 s0, s78
	s_bitcmp0_b32 s0, 0
	s_cselect_b64 s[8:9], -1, 0
	v_readlane_b32 s1, v219, 10
	v_readlane_b32 s2, v219, 11
	v_readlane_b32 s3, v219, 12
	v_readlane_b32 s4, v219, 13
	v_readlane_b32 s5, v219, 14
	v_readlane_b32 s6, v219, 15
	v_readlane_b32 s7, v219, 16
	v_readlane_b32 s10, v219, 19
	v_readlane_b32 s11, v219, 20
	v_readlane_b32 s12, v219, 21
	v_readlane_b32 s13, v219, 22
	v_readlane_b32 s14, v219, 23
	v_readlane_b32 s15, v219, 24
	s_waitcnt vmcnt(2)
	v_mul_f32_e32 v6, v0, v1
	ds_bpermute_b32 v6, v172, v6
	s_waitcnt vmcnt(0)
	v_mul_f32_e32 v12, v2, v3
	ds_bpermute_b32 v12, v172, v12
	s_waitcnt lgkmcnt(1)
	v_fmac_f32_e32 v6, v0, v1
	ds_bpermute_b32 v0, v173, v6
	s_waitcnt lgkmcnt(1)
	v_fmac_f32_e32 v12, v2, v3
	ds_bpermute_b32 v1, v173, v12
	v_cndmask_b32_e32 v2, v4, v8, vcc
	v_lshlrev_b32_e32 v174, 2, v2
	s_waitcnt lgkmcnt(1)
	v_add_f32_e32 v0, v6, v0
	ds_bpermute_b32 v2, v174, v0
	s_waitcnt lgkmcnt(1)
	v_add_f32_e32 v1, v12, v1
	ds_bpermute_b32 v3, v174, v1
	v_cmp_lt_i32_e32 vcc, v9, v5
	s_waitcnt lgkmcnt(1)
	v_add_f32_e32 v0, v0, v2
	v_cndmask_b32_e32 v6, v4, v9, vcc
	v_lshlrev_b32_e32 v175, 2, v6
	s_waitcnt lgkmcnt(0)
	v_add_f32_e32 v1, v1, v3
	ds_bpermute_b32 v2, v175, v0
	ds_bpermute_b32 v3, v175, v1
	v_cmp_lt_i32_e32 vcc, v10, v5
	s_waitcnt lgkmcnt(1)
	v_add_f32_e32 v0, v0, v2
	v_cndmask_b32_e32 v6, v4, v10, vcc
	v_lshlrev_b32_e32 v176, 2, v6
	s_waitcnt lgkmcnt(0)
	v_add_f32_e32 v1, v1, v3
	ds_bpermute_b32 v2, v176, v0
	ds_bpermute_b32 v3, v176, v1
	v_cmp_lt_i32_e32 vcc, v11, v5
	s_waitcnt lgkmcnt(1)
	v_add_f32_e32 v21, v0, v2
	v_cndmask_b32_e32 v4, v4, v11, vcc
	v_lshlrev_b32_e32 v177, 2, v4
	s_waitcnt lgkmcnt(0)
	v_add_f32_e32 v22, v1, v3
	ds_bpermute_b32 v23, v177, v21
	ds_bpermute_b32 v24, v177, v22
	s_and_b64 vcc, exec, s[8:9]
	s_cbranch_vccnz .LBB0_347
	s_add_i32 s0, s78, 0xc0
	s_cmpk_gt_i32 s0, 0x30f
	s_waitcnt lgkmcnt(0)
	s_barrier
	s_cbranch_scc1 .LBB0_346
	s_movk_i32 s1, 0x2100
	v_lshrrev_b32_e32 v25, 3, v149
	v_and_b32_e32 v4, 56, v144
	s_cmpk_eq_i32 s58, 0x100
	v_mad_u32_u24 v1, v148, s1, 0
	v_lshrrev_b32_e32 v0, 5, v149
	v_and_b32_e32 v2, 31, v168
	v_mul_u32_u24_e32 v3, 0x84, v4
	v_lshlrev_b32_e32 v7, 2, v25
	s_cselect_b64 s[6:7], -1, 0
	v_mov_b32_e32 v5, 0
	v_lshl_add_u32 v6, v2, 2, v1
	s_movk_i32 s1, 0x84
	v_add3_u32 v26, v1, v3, v7
	v_or_b32_e32 v27, 8, v25
	v_or_b32_e32 v28, 16, v25
	v_or_b32_e32 v29, 24, v25
	v_mov_b32_e32 v1, v0
	s_movk_i32 s2, 0x187f
	s_movk_i32 s3, 0x1ff
	s_movk_i32 s10, 0xcff
	v_lshlrev_b32_e32 v8, 2, v2
	v_lshlrev_b32_e32 v10, 1, v4
	v_mov_b32_e32 v30, 0xffffe780
	v_mov_b32_e32 v31, 0xc00
	v_mov_b32_e32 v32, 0x600
	v_mov_b32_e32 v33, 0x2c0000
	v_mov_b32_e32 v34, 0x1400000
	v_mov_b32_e32 v35, 0x2980000
	v_mov_b32_e32 v36, 0x900000
	v_mov_b32_e32 v37, 0x1e80000
	v_mov_b32_e32 v38, 0x700000
	v_mov_b32_e32 v39, 0x1c80000
	v_mov_b32_e32 v40, 0x100000
	v_mov_b32_e32 v41, 0x1980000
	s_branch .LBB0_330

.LBB0_360:
	v_exp_f32_e32 v76, v76
	v_exp_f32_e32 v77, v77
	v_exp_f32_e32 v78, v78
	v_exp_f32_e32 v79, v79
	v_exp_f32_e32 v74, v74
	v_exp_f32_e32 v75, v75
	v_exp_f32_e32 v84, v64
	v_exp_f32_e32 v85, v65
	v_exp_f32_e32 v86, v66
	v_exp_f32_e32 v87, v67
	v_exp_f32_e32 v72, v72
	v_exp_f32_e32 v73, v73
	v_exp_f32_e32 v80, v68
	v_exp_f32_e32 v81, v69
	v_exp_f32_e32 v82, v70
	v_exp_f32_e32 v83, v71
	v_cvt_pk_bf16_f32 v64, v76, v77
	v_cvt_pk_bf16_f32 v65, v78, v79
	v_cvt_pk_bf16_f32 v67, v74, v75
	v_cvt_pk_bf16_f32 v74, v84, v85
	ds_read_b64_tr_b16 v[78:79], v199 offset:20992
	ds_read_b64_tr_b16 v[76:77], v199 offset:16384
	v_cvt_pk_bf16_f32 v75, v86, v87
	ds_read_b64_tr_b16 v[84:85], v199 offset:16416
	ds_read_b64_tr_b16 v[88:89], v199 offset:16448
	ds_read_b64_tr_b16 v[92:93], v199 offset:16480
	ds_read_b64_tr_b16 v[86:87], v199 offset:21024
	ds_read_b64_tr_b16 v[90:91], v199 offset:21056
	ds_read_b64_tr_b16 v[94:95], v199 offset:21088
	v_mov_b32_e32 v57, v56
	v_mov_b32_e32 v58, v56
	v_mov_b32_e32 v59, v56
	v_mov_b32_e32 v61, v60
	v_mov_b32_e32 v62, v60
	v_mov_b32_e32 v63, v60
	v_cvt_pk_bf16_f32 v66, v72, v73
	v_cvt_pk_bf16_f32 v72, v80, v81
	v_cvt_pk_bf16_f32 v73, v82, v83
	s_waitcnt lgkmcnt(1)
	v_mfma_f32_16x16x32_bf16 v[104:107], v[88:91], v[64:67], v[56:59]
	v_exp_f32_e32 v48, v48
	v_exp_f32_e32 v49, v49
	v_exp_f32_e32 v50, v50
	v_mfma_f32_16x16x32_bf16 v[108:111], v[88:91], v[72:75], v[60:63]
	ds_read_b64_tr_b16 v[88:89], v199 offset:16512
	ds_read_b64_tr_b16 v[90:91], v199 offset:21120
	v_exp_f32_e32 v51, v51
	v_exp_f32_e32 v44, v44
	s_waitcnt lgkmcnt(2)
	v_mfma_f32_16x16x32_bf16 v[112:115], v[92:95], v[64:67], v[56:59]
	v_exp_f32_e32 v45, v45
	v_exp_f32_e32 v52, v52
	v_exp_f32_e32 v53, v53
	v_mfma_f32_16x16x32_bf16 v[116:119], v[92:95], v[72:75], v[60:63]
	ds_read_b64_tr_b16 v[92:93], v199 offset:16544
	ds_read_b64_tr_b16 v[120:121], v199 offset:16576
	ds_read_b64_tr_b16 v[124:125], v199 offset:16608
	ds_read_b64_tr_b16 v[94:95], v199 offset:21152
	ds_read_b64_tr_b16 v[122:123], v199 offset:21184
	ds_read_b64_tr_b16 v[126:127], v199 offset:21216
	v_exp_f32_e32 v54, v54
	v_exp_f32_e32 v55, v55
	v_mfma_f32_16x16x32_bf16 v[68:71], v[0:3], v[64:67], v[56:59]
	v_exp_f32_e32 v40, v40
	v_exp_f32_e32 v41, v41
	v_exp_f32_e32 v42, v42
	v_mfma_f32_16x16x32_bf16 v[96:99], v[76:79], v[64:67], v[56:59]
	v_exp_f32_e32 v43, v43
	v_cvt_pk_bf16_f32 v212, v44, v45
	v_cvt_pk_bf16_f32 v210, v40, v41
	v_mfma_f32_16x16x32_bf16 v[100:103], v[84:87], v[64:67], v[56:59]
	v_cvt_pk_bf16_f32 v211, v42, v43
	s_or_b32 s21, s20, s14
	s_add_i32 s25, s20, s14
	s_waitcnt lgkmcnt(6)
	v_mfma_f32_16x16x32_bf16 v[128:131], v[88:91], v[64:67], v[56:59]
	s_mov_b32 s27, 1
	s_waitcnt lgkmcnt(2)
	v_mfma_f32_16x16x32_bf16 v[136:139], v[92:95], v[64:67], v[56:59]
	s_waitcnt lgkmcnt(1)
	v_mfma_f32_16x16x32_bf16 v[202:205], v[120:123], v[64:67], v[56:59]
	s_waitcnt lgkmcnt(0)
	v_mfma_f32_16x16x32_bf16 v[206:209], v[124:127], v[64:67], v[56:59]
	s_nop 2
	v_exp_f32_e32 v56, v46
	v_exp_f32_e32 v57, v47
	v_mfma_f32_16x16x32_bf16 v[80:83], v[0:3], v[72:75], v[60:63]
	ds_read_b64_tr_b16 v[44:45], v199 offset:25600
	ds_read_b64_tr_b16 v[46:47], v199 offset:30208
	v_cvt_pk_bf16_f32 v213, v56, v57
	v_mfma_f32_16x16x32_bf16 v[76:79], v[76:79], v[72:75], v[60:63]
	v_mfma_f32_16x16x32_bf16 v[84:87], v[84:87], v[72:75], v[60:63]
	v_mfma_f32_16x16x32_bf16 v[132:135], v[88:91], v[72:75], v[60:63]
	v_mfma_f32_16x16x32_bf16 v[140:143], v[92:95], v[72:75], v[60:63]
	v_mfma_f32_16x16x32_bf16 v[120:123], v[120:123], v[72:75], v[60:63]
	v_mfma_f32_16x16x32_bf16 v[72:75], v[124:127], v[72:75], v[60:63]
	v_cvt_pk_bf16_f32 v126, v48, v49
	v_cvt_pk_bf16_f32 v127, v50, v51
	ds_read_b64_tr_b16 v[48:49], v199 offset:25632
	ds_read_b64_tr_b16 v[56:57], v199 offset:25664
	ds_read_b64_tr_b16 v[64:65], v199 offset:25696
	ds_read_b64_tr_b16 v[50:51], v199 offset:30240
	ds_read_b64_tr_b16 v[58:59], v199 offset:30272
	ds_read_b64_tr_b16 v[66:67], v199 offset:30304
	v_cvt_pk_bf16_f32 v124, v52, v53
	v_cvt_pk_bf16_f32 v125, v54, v55
	v_mfma_f32_16x16x32_bf16 v[40:43], v[0:3], v[210:213], v[80:83]
	s_nop 0
	v_mfma_f32_16x16x32_bf16 v[60:63], v[0:3], v[124:127], v[68:71]
	s_nop 2
	ds_read_b64_tr_b16 v[68:69], v199 offset:25728
	ds_read_b64_tr_b16 v[70:71], v199 offset:30336
	s_waitcnt lgkmcnt(8)
	v_mfma_f32_16x16x32_bf16 v[92:95], v[44:47], v[124:127], v[96:99]
	v_mfma_f32_16x16x32_bf16 v[52:55], v[44:47], v[210:213], v[76:79]
	s_waitcnt lgkmcnt(4)
	v_mfma_f32_16x16x32_bf16 v[88:91], v[48:51], v[124:127], v[100:103]
	v_mfma_f32_16x16x32_bf16 v[48:51], v[48:51], v[210:213], v[84:87]
	s_waitcnt lgkmcnt(3)
	v_mfma_f32_16x16x32_bf16 v[80:83], v[56:59], v[124:127], v[104:107]
	v_mfma_f32_16x16x32_bf16 v[44:47], v[56:59], v[210:213], v[108:111]
	s_waitcnt lgkmcnt(2)
	v_mfma_f32_16x16x32_bf16 v[84:87], v[64:67], v[124:127], v[112:115]
	v_mfma_f32_16x16x32_bf16 v[56:59], v[64:67], v[210:213], v[116:119]
	ds_read_b64_tr_b16 v[64:65], v199 offset:25760
	ds_read_b64_tr_b16 v[100:101], v199 offset:25792
	ds_read_b64_tr_b16 v[112:113], v199 offset:25824
	ds_read_b64_tr_b16 v[66:67], v199 offset:30368
	ds_read_b64_tr_b16 v[102:103], v199 offset:30400
	ds_read_b64_tr_b16 v[114:115], v199 offset:30432
	s_waitcnt vmcnt(3)
	ds_write_b128 v195, v[24:27] offset:34816
	s_waitcnt vmcnt(2)
	ds_write_b128 v196, v[28:31] offset:51200
	s_waitcnt vmcnt(1)
	ds_write_b128 v195, v[32:35] offset:38912
	s_waitcnt vmcnt(0)
	ds_write_b128 v196, v[36:39] offset:60416
	s_waitcnt lgkmcnt(10)
	v_mfma_f32_16x16x32_bf16 v[108:111], v[68:71], v[124:127], v[128:131]
	s_waitcnt lgkmcnt(0)
	s_barrier
	v_mfma_f32_16x16x32_bf16 v[76:79], v[68:71], v[210:213], v[132:135]
	v_mfma_f32_16x16x32_bf16 v[104:107], v[64:67], v[124:127], v[136:139]
	v_mfma_f32_16x16x32_bf16 v[64:67], v[64:67], v[210:213], v[140:143]
	v_mfma_f32_16x16x32_bf16 v[96:99], v[100:103], v[124:127], v[202:205]
	v_mfma_f32_16x16x32_bf16 v[68:71], v[100:103], v[210:213], v[120:123]
	v_mfma_f32_16x16x32_bf16 v[100:103], v[112:115], v[124:127], v[206:209]
	v_mfma_f32_16x16x32_bf16 v[72:75], v[112:115], v[210:213], v[72:75]
	s_cmp_eq_u32 s99, 0
	s_cbranch_scc1 .Latt0_noX
	s_barrier
.Latt0_noX:
.LBB0_361:
	s_add_i32 s26, s27, 1
	s_cmp_lt_u32 s26, s21
	s_cselect_b64 s[48:49], -1, 0
	s_cmp_ge_u32 s26, s21
	s_cbranch_scc1 .LBB0_363
	s_cmp_lg_u32 s99, 0
	s_cbranch_scc1 .LBB0_363
	s_cmp_lt_u32 s26, s20
	s_cselect_b64 s[28:29], -1, 0
	s_and_b64 s[50:51], s[28:29], exec
	s_cselect_b32 s14, 0, s20
	s_sub_i32 s14, s27, s14
	s_add_i32 s14, s14, 1
	s_and_b64 s[50:51], s[28:29], exec
	s_cselect_b32 s33, s47, s13
	s_cselect_b32 s41, s46, s12
	s_lshl_b64 s[50:51], s[14:15], 17
	s_add_u32 s60, s41, s50
	s_addc_u32 s61, s33, s51
	s_and_b64 s[28:29], s[28:29], exec
	s_cselect_b32 s28, s44, s42
	s_cselect_b32 s14, s45, s43
	s_add_u32 s28, s28, s50
	s_waitcnt vmcnt(1)
	v_lshl_add_u64 v[32:33], s[60:61], 0, v[152:153]
	s_addc_u32 s29, s14, s51
	v_add_co_u32_e32 v32, vcc, 0x10000, v32
	s_waitcnt vmcnt(0)
	v_lshl_add_u64 v[36:37], s[28:29], 0, v[152:153]
	v_addc_co_u32_e32 v33, vcc, 0, v33, vcc
	v_add_co_u32_e32 v36, vcc, 0x10000, v36
	global_load_dwordx4 v[24:27], v152, s[60:61]
	global_load_dwordx4 v[28:31], v152, s[28:29]
	v_addc_co_u32_e32 v37, vcc, 0, v37, vcc
	global_load_dwordx4 v[32:35], v[32:33], off
	s_nop 0
	global_load_dwordx4 v[36:39], v[36:37], off
	s_add_u32 s100, s60, 0x8000
	s_addc_u32 s101, s61, 0
	global_load_dwordx4 v[220:223], v152, s[100:101]
	s_add_u32 s100, s28, 0x8000
	s_addc_u32 s101, s29, 0
	global_load_dwordx4 v[224:227], v152, s[100:101]
	s_add_u32 s100, s60, 0x18000
	s_addc_u32 s101, s61, 0
	global_load_dwordx4 v[228:231], v152, s[100:101]
	s_add_u32 s100, s28, 0x18000
	s_addc_u32 s101, s29, 0
	global_load_dwordx4 v[232:235], v152, s[100:101]

.LBB0_367:
	v_exp_f32_e32 v140, v140
	v_exp_f32_e32 v141, v141
	v_exp_f32_e32 v142, v142
	v_exp_f32_e32 v143, v143
	v_exp_f32_e32 v136, v136
	v_exp_f32_e32 v137, v137
	v_exp_f32_e32 v138, v138
	v_exp_f32_e32 v139, v139
	v_exp_f32_e32 v132, v132
	v_exp_f32_e32 v133, v133
	v_exp_f32_e32 v134, v134
	v_exp_f32_e32 v135, v135
	v_exp_f32_e32 v202, v128
	v_exp_f32_e32 v203, v129
	v_exp_f32_e32 v204, v130
	v_exp_f32_e32 v205, v131
	v_add3_u32 v210, s14, v192, v193
	v_cvt_pk_bf16_f32 v128, v140, v141
	v_cvt_pk_bf16_f32 v129, v142, v143
	v_cvt_pk_bf16_f32 v130, v136, v137
	v_cvt_pk_bf16_f32 v131, v138, v139
	v_cvt_pk_bf16_f32 v132, v132, v133
	v_cvt_pk_bf16_f32 v133, v134, v135
	v_cvt_pk_bf16_f32 v134, v202, v203
	s_barrier
	ds_read_b64_tr_b16 v[138:139], v210 offset:20992
	ds_read_b64_tr_b16 v[136:137], v210 offset:16384
	v_cvt_pk_bf16_f32 v135, v204, v205
	ds_read_b64_tr_b16 v[140:141], v210 offset:16416
	ds_read_b64_tr_b16 v[202:203], v210 offset:16448
	ds_read_b64_tr_b16 v[206:207], v210 offset:16480
	ds_read_b64_tr_b16 v[142:143], v210 offset:21024
	ds_read_b64_tr_b16 v[204:205], v210 offset:21056
	ds_read_b64_tr_b16 v[208:209], v210 offset:21088
	s_waitcnt lgkmcnt(6)
	v_mfma_f32_16x16x32_bf16 v[92:95], v[136:139], v[128:131], v[92:95]
	v_exp_f32_e32 v112, v112
	v_exp_f32_e32 v113, v113
	v_exp_f32_e32 v114, v114
	v_mfma_f32_16x16x32_bf16 v[52:55], v[136:139], v[132:135], v[52:55]
	ds_read_b64_tr_b16 v[136:137], v210 offset:16512
	ds_read_b64_tr_b16 v[138:139], v210 offset:21120
	v_exp_f32_e32 v115, v115
	v_exp_f32_e32 v124, v124
	s_waitcnt lgkmcnt(4)
	v_mfma_f32_16x16x32_bf16 v[88:91], v[140:143], v[128:131], v[88:91]
	v_exp_f32_e32 v125, v125
	v_exp_f32_e32 v126, v126
	v_exp_f32_e32 v127, v127
	v_mfma_f32_16x16x32_bf16 v[48:51], v[140:143], v[132:135], v[48:51]
	v_exp_f32_e32 v116, v116
	v_exp_f32_e32 v117, v117
	v_exp_f32_e32 v118, v118
	s_waitcnt lgkmcnt(3)
	v_mfma_f32_16x16x32_bf16 v[80:83], v[202:205], v[128:131], v[80:83]
	v_exp_f32_e32 v119, v119
	v_exp_f32_e32 v120, v120
	v_exp_f32_e32 v121, v121
	v_mfma_f32_16x16x32_bf16 v[44:47], v[202:205], v[132:135], v[44:47]
	v_cvt_pk_bf16_f32 v112, v112, v113
	v_cvt_pk_bf16_f32 v113, v114, v115
	v_cvt_pk_bf16_f32 v114, v124, v125
	s_waitcnt lgkmcnt(2)
	v_mfma_f32_16x16x32_bf16 v[84:87], v[206:209], v[128:131], v[84:87]
	v_cvt_pk_bf16_f32 v115, v126, v127
	v_cvt_pk_bf16_f32 v116, v116, v117
	v_cvt_pk_bf16_f32 v117, v118, v119
	v_mfma_f32_16x16x32_bf16 v[56:59], v[206:209], v[132:135], v[56:59]
	ds_read_b64_tr_b16 v[140:141], v210 offset:16544
	ds_read_b64_tr_b16 v[202:203], v210 offset:16576
	ds_read_b64_tr_b16 v[206:207], v210 offset:16608
	ds_read_b64_tr_b16 v[142:143], v210 offset:21152
	ds_read_b64_tr_b16 v[204:205], v210 offset:21184
	ds_read_b64_tr_b16 v[208:209], v210 offset:21216
	v_cvt_pk_bf16_f32 v118, v120, v121
	s_andn2_b64 vcc, exec, s[48:49]
	v_mfma_f32_16x16x32_bf16 v[60:63], v[0:3], v[128:131], v[60:63]
	s_waitcnt lgkmcnt(6)
	v_mfma_f32_16x16x32_bf16 v[108:111], v[136:139], v[128:131], v[108:111]
	s_waitcnt lgkmcnt(2)
	v_mfma_f32_16x16x32_bf16 v[104:107], v[140:143], v[128:131], v[104:107]
	s_waitcnt lgkmcnt(1)
	v_mfma_f32_16x16x32_bf16 v[96:99], v[202:205], v[128:131], v[96:99]
	s_waitcnt lgkmcnt(0)
	v_mfma_f32_16x16x32_bf16 v[100:103], v[206:209], v[128:131], v[100:103]
	v_exp_f32_e32 v128, v122
	v_exp_f32_e32 v129, v123
	ds_read_b64_tr_b16 v[120:121], v210 offset:25600
	ds_read_b64_tr_b16 v[122:123], v210 offset:30208
	v_mfma_f32_16x16x32_bf16 v[40:43], v[0:3], v[132:135], v[40:43]
	v_cvt_pk_bf16_f32 v119, v128, v129
	v_mfma_f32_16x16x32_bf16 v[76:79], v[136:139], v[132:135], v[76:79]
	v_mfma_f32_16x16x32_bf16 v[64:67], v[140:143], v[132:135], v[64:67]
	v_mfma_f32_16x16x32_bf16 v[68:71], v[202:205], v[132:135], v[68:71]
	v_mfma_f32_16x16x32_bf16 v[72:75], v[206:209], v[132:135], v[72:75]
	ds_read_b64_tr_b16 v[124:125], v210 offset:25632
	ds_read_b64_tr_b16 v[128:129], v210 offset:25664
	ds_read_b64_tr_b16 v[132:133], v210 offset:25696
	ds_read_b64_tr_b16 v[126:127], v210 offset:30240
	ds_read_b64_tr_b16 v[130:131], v210 offset:30272
	ds_read_b64_tr_b16 v[134:135], v210 offset:30304
	s_waitcnt lgkmcnt(6)
	v_mfma_f32_16x16x32_bf16 v[92:95], v[120:123], v[112:115], v[92:95]
	v_mfma_f32_16x16x32_bf16 v[52:55], v[120:123], v[116:119], v[52:55]
	ds_read_b64_tr_b16 v[120:121], v210 offset:25728
	ds_read_b64_tr_b16 v[122:123], v210 offset:30336
	s_waitcnt lgkmcnt(4)
	v_mfma_f32_16x16x32_bf16 v[88:91], v[124:127], v[112:115], v[88:91]
	v_mfma_f32_16x16x32_bf16 v[48:51], v[124:127], v[116:119], v[48:51]
	s_waitcnt lgkmcnt(3)
	v_mfma_f32_16x16x32_bf16 v[80:83], v[128:131], v[112:115], v[80:83]
	v_mfma_f32_16x16x32_bf16 v[44:47], v[128:131], v[116:119], v[44:47]
	s_waitcnt lgkmcnt(2)
	v_mfma_f32_16x16x32_bf16 v[84:87], v[132:135], v[112:115], v[84:87]
	v_mfma_f32_16x16x32_bf16 v[56:59], v[132:135], v[116:119], v[56:59]
	ds_read_b64_tr_b16 v[124:125], v210 offset:25760
	ds_read_b64_tr_b16 v[128:129], v210 offset:25792
	ds_read_b64_tr_b16 v[132:133], v210 offset:25824
	ds_read_b64_tr_b16 v[126:127], v210 offset:30368
	ds_read_b64_tr_b16 v[130:131], v210 offset:30400
	ds_read_b64_tr_b16 v[134:135], v210 offset:30432
	v_mfma_f32_16x16x32_bf16 v[60:63], v[0:3], v[112:115], v[60:63]
	v_mfma_f32_16x16x32_bf16 v[40:43], v[0:3], v[116:119], v[40:43]
	s_waitcnt lgkmcnt(6)
	v_mfma_f32_16x16x32_bf16 v[108:111], v[120:123], v[112:115], v[108:111]
	v_mfma_f32_16x16x32_bf16 v[76:79], v[120:123], v[116:119], v[76:79]
	s_waitcnt lgkmcnt(2)
	v_mfma_f32_16x16x32_bf16 v[104:107], v[124:127], v[112:115], v[104:107]
	v_mfma_f32_16x16x32_bf16 v[64:67], v[124:127], v[116:119], v[64:67]
	s_waitcnt lgkmcnt(1)
	v_mfma_f32_16x16x32_bf16 v[96:99], v[128:131], v[112:115], v[96:99]
	v_mfma_f32_16x16x32_bf16 v[68:71], v[128:131], v[116:119], v[68:71]
	s_waitcnt lgkmcnt(0)
	v_mfma_f32_16x16x32_bf16 v[100:103], v[132:135], v[112:115], v[100:103]
	v_mfma_f32_16x16x32_bf16 v[72:75], v[132:135], v[116:119], v[72:75]
	s_cbranch_vccnz .LBB0_369
	s_cmp_lg_u32 s99, 0
	s_cbranch_scc1 .LBB0_369
	s_bitcmp1_b32 s26, 0
	s_cselect_b32 s14, 0x8800, 0
	s_add_i32 s14, s14, 0
	v_add_u32_e32 v113, s14, v185
	v_add_u32_e32 v112, s14, v188
	s_waitcnt vmcnt(0)
	ds_write_b128 v113, v[24:27]
	ds_write_b128 v112, v[28:31] offset:16384
	ds_write_b128 v113, v[32:35] offset:4096
	ds_write_b128 v112, v[36:39] offset:25600
	ds_write_b128 v113, v[220:223] offset:2048
	ds_write_b128 v112, v[224:227] offset:20992
	ds_write_b128 v113, v[228:231] offset:6144
	ds_write_b128 v112, v[232:235] offset:30208

.LBB0_371:
	s_cmp_lg_u32 s99, 0
	s_cbranch_scc1 .Latt0_noZ
	s_barrier
